# plus: rotary (q/k) projection epilogue rewritten: row-stat loads batched, cos/sin table rows double-buffered two row-groups ahead, 24 serial round trips removed
# speedup vs baseline: 1.0049x; 1.0049x over previous
;     __device__ __forceinline__ void operator()(const pg8::f32x4 (&acc)[2][2][4][2], const pg8::Unit& u, int wr, int wc, int fr, int fq) const {
;     ...
;             const float ksc = u.pn >= 11 ? 0.08838834764831845f : 1.0f;
;             const int d0 = 32 * (wc & 1) + 8 * fq, colr = u.pn * 256 + 128 * (wc >> 1) + d0;
; #pragma unroll
;             for (int ai = 0; ai < 2; ++ai)
; #pragma unroll
;                 for (int m = 0; m < 4; ++m) {
;                     const size_t row = (size_t)(row0 + ai * 128 + m * 16);
;                     const int gr = (int)row + row_off, pos = gr < 65536 ? (gr & 8191) : (gr & 4095);
;                     const float rs = row_rs4(ssq, (size_t)gr, fq) * ksc;
.LBB0_182:
	v_readlane_b32 s16, v253, 22
	s_cmp_gt_u32 s34, 10
	v_and_b32_e32 v151, 64, v175
	v_xor_b32_e32 v153, 16, v175
	v_add_u32_e32 v151, 64, v151
	s_cselect_b64 s[0:1], -1, 0
	v_mov_b32_e32 v128, 0x3db504f3
	v_cmp_lt_i32_e32 vcc, v153, v151
	v_xor_b32_e32 v155, 32, v175
	s_mov_b32 s11, 0x800000
	v_cndmask_b32_e32 v153, v175, v153, vcc
	v_cmp_lt_i32_e32 vcc, v155, v151
	v_lshlrev_b32_e32 v153, 2, v153
	v_cndmask_b32_e64 v157, 1.0, v128, s[0:1]
	v_cndmask_b32_e32 v155, v175, v155, vcc
	v_lshlrev_b32_e32 v155, 2, v155
	v_or_b32_e32 v128, s9, v197
	v_readlane_b32 s0, v253, 38
	v_readlane_b32 s1, v253, 39
	v_lshlrev_b32_e32 v248, 1, v128
	v_add_u32_e32 v176, s16, v164
	v_ashrrev_i32_e32 v177, 31, v176
	v_lshlrev_b64 v[176:177], 6, v[176:177]
	v_lshl_add_u64 v[176:177], v[140:141], 0, v[176:177]
	global_load_dwordx4 v[200:203], v[176:177], off
	v_add_u32_e32 v176, s16, v162
	v_ashrrev_i32_e32 v177, 31, v176
	v_lshlrev_b64 v[176:177], 6, v[176:177]
	v_lshl_add_u64 v[176:177], v[140:141], 0, v[176:177]
	global_load_dwordx4 v[204:207], v[176:177], off
	v_add_u32_e32 v176, s16, v160
	v_ashrrev_i32_e32 v177, 31, v176
	v_lshlrev_b64 v[176:177], 6, v[176:177]
	v_lshl_add_u64 v[176:177], v[140:141], 0, v[176:177]
	global_load_dwordx4 v[208:211], v[176:177], off
	v_add_u32_e32 v176, s16, v158
	v_ashrrev_i32_e32 v177, 31, v176
	v_lshlrev_b64 v[176:177], 6, v[176:177]
	v_lshl_add_u64 v[176:177], v[140:141], 0, v[176:177]
	global_load_dwordx4 v[212:215], v[176:177], off
	v_add_u32_e32 v176, s16, v156
	v_ashrrev_i32_e32 v177, 31, v176
	v_lshlrev_b64 v[176:177], 6, v[176:177]
	v_lshl_add_u64 v[176:177], v[140:141], 0, v[176:177]
	global_load_dwordx4 v[216:219], v[176:177], off
	v_add_u32_e32 v176, s16, v154
	v_ashrrev_i32_e32 v177, 31, v176
	v_lshlrev_b64 v[176:177], 6, v[176:177]
	v_lshl_add_u64 v[176:177], v[140:141], 0, v[176:177]
	global_load_dwordx4 v[220:223], v[176:177], off
	v_add_u32_e32 v176, s16, v152
	v_ashrrev_i32_e32 v177, 31, v176
	v_lshlrev_b64 v[176:177], 6, v[176:177]
	v_lshl_add_u64 v[176:177], v[140:141], 0, v[176:177]
	global_load_dwordx4 v[224:227], v[176:177], off
	v_add_u32_e32 v176, s16, v150
	v_ashrrev_i32_e32 v177, 31, v176
	v_lshlrev_b64 v[176:177], 6, v[176:177]
	v_lshl_add_u64 v[176:177], v[140:141], 0, v[176:177]
	global_load_dwordx4 v[228:231], v[176:177], off
	s_waitcnt vmcnt(0)
	v_add_f32_e32 v232, v201, v200
	v_add_f32_e32 v240, v202, v203
	v_add_f32_e32 v232, v232, v240
	v_add_f32_e32 v233, v205, v204
	v_add_f32_e32 v241, v206, v207
	v_add_f32_e32 v233, v233, v241
	v_add_f32_e32 v234, v209, v208
	v_add_f32_e32 v242, v210, v211
	v_add_f32_e32 v234, v234, v242
	v_add_f32_e32 v235, v213, v212
	v_add_f32_e32 v243, v214, v215
	v_add_f32_e32 v235, v235, v243
	v_add_f32_e32 v236, v217, v216
	v_add_f32_e32 v244, v218, v219
	v_add_f32_e32 v236, v236, v244
	v_add_f32_e32 v237, v221, v220
	v_add_f32_e32 v245, v222, v223
	v_add_f32_e32 v237, v237, v245
	v_add_f32_e32 v238, v225, v224
	v_add_f32_e32 v246, v226, v227
	v_add_f32_e32 v238, v238, v246
	v_add_f32_e32 v239, v229, v228
	v_add_f32_e32 v247, v230, v231
	v_add_f32_e32 v239, v239, v247
	v_add_u32_e32 v178, s16, v164
	v_cmp_gt_i32_e32 vcc, 0x10000, v178
	v_mov_b32_e32 v179, 0
	v_mov_b32_e32 v177, 0x1fff
	v_mov_b32_e32 v176, 0xfff
	v_cndmask_b32_e32 v176, v176, v177, vcc
	v_and_b32_e32 v178, v176, v178
	v_lshlrev_b32_e32 v178, 8, v178
	v_lshl_add_u64 v[176:177], v[142:143], 0, v[178:179]
	global_load_dwordx4 v[200:203], v[176:177], off
	global_load_dwordx4 v[208:211], v[176:177], off offset:16
	v_lshl_add_u64 v[176:177], v[144:145], 0, v[178:179]
	global_load_dwordx4 v[204:207], v[176:177], off
	global_load_dwordx4 v[212:215], v[176:177], off offset:16
	v_add_u32_e32 v178, s16, v162
	v_cmp_gt_i32_e32 vcc, 0x10000, v178
	v_mov_b32_e32 v179, 0
	v_mov_b32_e32 v177, 0x1fff
	v_mov_b32_e32 v176, 0xfff
	v_cndmask_b32_e32 v176, v176, v177, vcc
	v_and_b32_e32 v178, v176, v178
	v_lshlrev_b32_e32 v178, 8, v178
	v_lshl_add_u64 v[176:177], v[142:143], 0, v[178:179]
	global_load_dwordx4 v[216:219], v[176:177], off
	global_load_dwordx4 v[224:227], v[176:177], off offset:16
	v_lshl_add_u64 v[176:177], v[144:145], 0, v[178:179]
	global_load_dwordx4 v[220:223], v[176:177], off
	global_load_dwordx4 v[228:231], v[176:177], off offset:16
	ds_bpermute_b32 v240, v153, v232
	ds_bpermute_b32 v241, v153, v233
	ds_bpermute_b32 v242, v153, v234
	ds_bpermute_b32 v243, v153, v235
	ds_bpermute_b32 v244, v153, v236
	ds_bpermute_b32 v245, v153, v237
	ds_bpermute_b32 v246, v153, v238
	ds_bpermute_b32 v247, v153, v239
	s_waitcnt lgkmcnt(0)
	v_add_f32_e32 v232, v232, v240
	v_add_f32_e32 v233, v233, v241
	v_add_f32_e32 v234, v234, v242
	v_add_f32_e32 v235, v235, v243
	v_add_f32_e32 v236, v236, v244
	v_add_f32_e32 v237, v237, v245
	v_add_f32_e32 v238, v238, v246
	v_add_f32_e32 v239, v239, v247
	ds_bpermute_b32 v240, v155, v232
	ds_bpermute_b32 v241, v155, v233
	ds_bpermute_b32 v242, v155, v234
	ds_bpermute_b32 v243, v155, v235
	ds_bpermute_b32 v244, v155, v236
	ds_bpermute_b32 v245, v155, v237
	ds_bpermute_b32 v246, v155, v238
	ds_bpermute_b32 v247, v155, v239
	s_waitcnt lgkmcnt(0)
; __device__ __forceinline__ unsigned pk2(float lo, float hi) { return pg8::cvt_pk_bf16(lo, hi); }
;     __device__ __forceinline__ void operator()(const pg8::f32x4 (&acc)[2][2][4][2], const pg8::Unit& u, int wr, int wc, int fr, int fq) const {
;     ...
;                     const size_t row = (size_t)(row0 + ai * 128 + m * 16);
;                     const int gr = (int)row + row_off, pos = gr < 65536 ? (gr & 8191) : (gr & 4095);
;                     const float rs = row_rs4(ssq, (size_t)gr, fq) * ksc;
;                     u32x4 w1, w2;
; #pragma unroll
;                     for (int n = 0; n < 2; ++n) {
;                         const pg8::f32x4 cs = *(const pg8::f32x4*)(rcos + (size_t)pos * 64 + d0 + 4 * n), sn = *(const pg8::f32x4*)(rsin + (size_t)pos * 64 + d0 + 4 * n);
;                         const pg8::f32x4 t1 = acc[ai][0][m][n] * rs, t2 = acc[ai][1][m][n] * rs;
;                         const pg8::f32x4 o1 = t1 * cs - t2 * sn, o2 = t1 * sn + t2 * cs;
;                         if (n == 0) { w1.x = pk2(o1[0], o1[1]); w1.y = pk2(o1[2], o1[3]); w2.x = pk2(o2[0], o2[1]); w2.y = pk2(o2[2], o2[3]); }
;                         else { w1.z = pk2(o1[0], o1[1]); w1.w = pk2(o1[2], o1[3]); w2.z = pk2(o2[0], o2[1]); w2.w = pk2(o2[2], o2[3]); }
;                     }
;                     *(u32x4*)(P + row * PLD + colr) = w1; *(u32x4*)(P + row * PLD + colr + 64) = w2;
	v_add_f32_e32 v232, v232, v240
	v_add_f32_e32 v233, v233, v241
	v_add_f32_e32 v234, v234, v242
	v_add_f32_e32 v235, v235, v243
	v_add_f32_e32 v236, v236, v244
	v_add_f32_e32 v237, v237, v245
	v_add_f32_e32 v238, v238, v246
	v_add_f32_e32 v239, v239, v247
	v_fmamk_f32 v232, v232, 0x3a800000, v171
	v_cmp_gt_f32_e32 vcc, s11, v232
	v_mul_f32_e32 v240, 0x4b800000, v232
	s_nop 0
	v_cndmask_b32_e32 v232, v232, v240, vcc
	v_rsq_f32_e32 v232, v232
	s_nop 0
	v_mul_f32_e32 v240, 0x45800000, v232
	v_cndmask_b32_e32 v232, v232, v240, vcc
	v_mul_f32_e32 v232, v157, v232
	v_fmamk_f32 v233, v233, 0x3a800000, v171
	v_cmp_gt_f32_e32 vcc, s11, v233
	v_mul_f32_e32 v241, 0x4b800000, v233
	s_nop 0
	v_cndmask_b32_e32 v233, v233, v241, vcc
	v_rsq_f32_e32 v233, v233
	s_nop 0
	v_mul_f32_e32 v241, 0x45800000, v233
	v_cndmask_b32_e32 v233, v233, v241, vcc
	v_mul_f32_e32 v233, v157, v233
	v_fmamk_f32 v234, v234, 0x3a800000, v171
	v_cmp_gt_f32_e32 vcc, s11, v234
	v_mul_f32_e32 v242, 0x4b800000, v234
	s_nop 0
	v_cndmask_b32_e32 v234, v234, v242, vcc
	v_rsq_f32_e32 v234, v234
	s_nop 0
	v_mul_f32_e32 v242, 0x45800000, v234
	v_cndmask_b32_e32 v234, v234, v242, vcc
	v_mul_f32_e32 v234, v157, v234
	v_fmamk_f32 v235, v235, 0x3a800000, v171
	v_cmp_gt_f32_e32 vcc, s11, v235
	v_mul_f32_e32 v243, 0x4b800000, v235
	s_nop 0
	v_cndmask_b32_e32 v235, v235, v243, vcc
	v_rsq_f32_e32 v235, v235
	s_nop 0
	v_mul_f32_e32 v243, 0x45800000, v235
	v_cndmask_b32_e32 v235, v235, v243, vcc
	v_mul_f32_e32 v235, v157, v235
	v_fmamk_f32 v236, v236, 0x3a800000, v171
	v_cmp_gt_f32_e32 vcc, s11, v236
	v_mul_f32_e32 v244, 0x4b800000, v236
	s_nop 0
	v_cndmask_b32_e32 v236, v236, v244, vcc
	v_rsq_f32_e32 v236, v236
	s_nop 0
	v_mul_f32_e32 v244, 0x45800000, v236
	v_cndmask_b32_e32 v236, v236, v244, vcc
	v_mul_f32_e32 v236, v157, v236
	v_fmamk_f32 v237, v237, 0x3a800000, v171
	v_cmp_gt_f32_e32 vcc, s11, v237
	v_mul_f32_e32 v245, 0x4b800000, v237
	s_nop 0
	v_cndmask_b32_e32 v237, v237, v245, vcc
	v_rsq_f32_e32 v237, v237
	s_nop 0
	v_mul_f32_e32 v245, 0x45800000, v237
	v_cndmask_b32_e32 v237, v237, v245, vcc
	v_mul_f32_e32 v237, v157, v237
	v_fmamk_f32 v238, v238, 0x3a800000, v171
	v_cmp_gt_f32_e32 vcc, s11, v238
	v_mul_f32_e32 v246, 0x4b800000, v238
	s_nop 0
	v_cndmask_b32_e32 v238, v238, v246, vcc
	v_rsq_f32_e32 v238, v238
	s_nop 0
	v_mul_f32_e32 v246, 0x45800000, v238
	v_cndmask_b32_e32 v238, v238, v246, vcc
	v_mul_f32_e32 v238, v157, v238
	v_fmamk_f32 v239, v239, 0x3a800000, v171
	v_cmp_gt_f32_e32 vcc, s11, v239
	v_mul_f32_e32 v247, 0x4b800000, v239
	s_nop 0
	v_cndmask_b32_e32 v239, v239, v247, vcc
	v_rsq_f32_e32 v239, v239
	s_nop 0
	v_mul_f32_e32 v247, 0x45800000, v239
	v_cndmask_b32_e32 v239, v239, v247, vcc
	v_mul_f32_e32 v239, v157, v239
	v_mov_b32_e32 v128, v232
	v_pk_mul_f32 v[124:125], v[124:125], v[128:129] op_sel_hi:[1,0]
	v_pk_mul_f32 v[126:127], v[126:127], v[128:129] op_sel_hi:[1,0]
	v_pk_mul_f32 v[120:121], v[120:121], v[128:129] op_sel_hi:[1,0]
	v_pk_mul_f32 v[122:123], v[122:123], v[128:129] op_sel_hi:[1,0]
	v_pk_mul_f32 v[116:117], v[116:117], v[128:129] op_sel_hi:[1,0]
	v_pk_mul_f32 v[118:119], v[118:119], v[128:129] op_sel_hi:[1,0]
	v_pk_mul_f32 v[112:113], v[112:113], v[128:129] op_sel_hi:[1,0]
	v_pk_mul_f32 v[114:115], v[114:115], v[128:129] op_sel_hi:[1,0]
	s_waitcnt vmcnt(4)
	v_pk_mul_f32 v[166:167], v[200:201], v[120:121]
	v_pk_mul_f32 v[240:241], v[204:205], v[120:121]
	v_pk_fma_f32 v[166:167], v[204:205], v[124:125], v[166:167] neg_lo:[0,0,1] neg_hi:[0,0,1]
	v_pk_fma_f32 v[240:241], v[200:201], v[124:125], v[240:241]
	v_pk_mul_f32 v[168:169], v[202:203], v[122:123]
	v_pk_mul_f32 v[242:243], v[206:207], v[122:123]
	v_pk_fma_f32 v[168:169], v[206:207], v[126:127], v[168:169] neg_lo:[0,0,1] neg_hi:[0,0,1]
	v_pk_fma_f32 v[242:243], v[202:203], v[126:127], v[242:243]
	v_pk_mul_f32 v[176:177], v[208:209], v[112:113]
	v_pk_mul_f32 v[244:245], v[212:213], v[112:113]
	v_pk_fma_f32 v[176:177], v[212:213], v[116:117], v[176:177] neg_lo:[0,0,1] neg_hi:[0,0,1]
	v_pk_fma_f32 v[244:245], v[208:209], v[116:117], v[244:245]
	v_pk_mul_f32 v[178:179], v[210:211], v[114:115]
	v_pk_mul_f32 v[246:247], v[214:215], v[114:115]
	v_pk_fma_f32 v[178:179], v[214:215], v[118:119], v[178:179] neg_lo:[0,0,1] neg_hi:[0,0,1]
	v_pk_fma_f32 v[246:247], v[210:211], v[118:119], v[246:247]
	v_cvt_pk_bf16_f32 v124, v166, v167
	v_cvt_pk_bf16_f32 v125, v168, v169
	v_cvt_pk_bf16_f32 v126, v176, v177
	v_cvt_pk_bf16_f32 v127, v178, v179
	v_cvt_pk_bf16_f32 v120, v240, v241
	v_cvt_pk_bf16_f32 v121, v242, v243
	v_cvt_pk_bf16_f32 v122, v244, v245
	v_cvt_pk_bf16_f32 v123, v246, v247
	v_mad_u32_u24 v128, v164, s57, v248
	global_store_dwordx4 v128, v[124:127], s[0:1]
	global_store_dwordx4 v128, v[120:123], s[0:1] offset:128
	v_add_u32_e32 v178, s16, v160
	v_cmp_gt_i32_e32 vcc, 0x10000, v178
	v_mov_b32_e32 v179, 0
	v_mov_b32_e32 v177, 0x1fff
	v_mov_b32_e32 v176, 0xfff
	v_cndmask_b32_e32 v176, v176, v177, vcc
	v_and_b32_e32 v178, v176, v178
	v_lshlrev_b32_e32 v178, 8, v178
	v_lshl_add_u64 v[176:177], v[142:143], 0, v[178:179]
	global_load_dwordx4 v[200:203], v[176:177], off
	global_load_dwordx4 v[208:211], v[176:177], off offset:16
	v_lshl_add_u64 v[176:177], v[144:145], 0, v[178:179]
	global_load_dwordx4 v[204:207], v[176:177], off
	global_load_dwordx4 v[212:215], v[176:177], off offset:16
	v_mov_b32_e32 v128, v233
	v_pk_mul_f32 v[108:109], v[108:109], v[128:129] op_sel_hi:[1,0]
	v_pk_mul_f32 v[110:111], v[110:111], v[128:129] op_sel_hi:[1,0]
	v_pk_mul_f32 v[104:105], v[104:105], v[128:129] op_sel_hi:[1,0]
	v_pk_mul_f32 v[106:107], v[106:107], v[128:129] op_sel_hi:[1,0]
	v_pk_mul_f32 v[100:101], v[100:101], v[128:129] op_sel_hi:[1,0]
	v_pk_mul_f32 v[102:103], v[102:103], v[128:129] op_sel_hi:[1,0]
	v_pk_mul_f32 v[96:97], v[96:97], v[128:129] op_sel_hi:[1,0]
	v_pk_mul_f32 v[98:99], v[98:99], v[128:129] op_sel_hi:[1,0]
	s_waitcnt vmcnt(6)
; __device__ __forceinline__ unsigned pk2(float lo, float hi) { return pg8::cvt_pk_bf16(lo, hi); }
;     __device__ __forceinline__ void operator()(const pg8::f32x4 (&acc)[2][2][4][2], const pg8::Unit& u, int wr, int wc, int fr, int fq) const {
;     ...
;                     u32x4 w1, w2;
; #pragma unroll
;                     for (int n = 0; n < 2; ++n) {
;                         const pg8::f32x4 cs = *(const pg8::f32x4*)(rcos + (size_t)pos * 64 + d0 + 4 * n), sn = *(const pg8::f32x4*)(rsin + (size_t)pos * 64 + d0 + 4 * n);
;                         const pg8::f32x4 t1 = acc[ai][0][m][n] * rs, t2 = acc[ai][1][m][n] * rs;
;                         const pg8::f32x4 o1 = t1 * cs - t2 * sn, o2 = t1 * sn + t2 * cs;
;                         if (n == 0) { w1.x = pk2(o1[0], o1[1]); w1.y = pk2(o1[2], o1[3]); w2.x = pk2(o2[0], o2[1]); w2.y = pk2(o2[2], o2[3]); }
;                         else { w1.z = pk2(o1[0], o1[1]); w1.w = pk2(o1[2], o1[3]); w2.z = pk2(o2[0], o2[1]); w2.w = pk2(o2[2], o2[3]); }
;                     }
;                     *(u32x4*)(P + row * PLD + colr) = w1; *(u32x4*)(P + row * PLD + colr + 64) = w2;
;                     asm volatile("" ::: "memory");
	v_pk_mul_f32 v[166:167], v[216:217], v[104:105]
	v_pk_mul_f32 v[240:241], v[220:221], v[104:105]
	v_pk_fma_f32 v[166:167], v[220:221], v[108:109], v[166:167] neg_lo:[0,0,1] neg_hi:[0,0,1]
	v_pk_fma_f32 v[240:241], v[216:217], v[108:109], v[240:241]
	v_pk_mul_f32 v[168:169], v[218:219], v[106:107]
	v_pk_mul_f32 v[242:243], v[222:223], v[106:107]
	v_pk_fma_f32 v[168:169], v[222:223], v[110:111], v[168:169] neg_lo:[0,0,1] neg_hi:[0,0,1]
	v_pk_fma_f32 v[242:243], v[218:219], v[110:111], v[242:243]
	v_pk_mul_f32 v[176:177], v[224:225], v[96:97]
	v_pk_mul_f32 v[244:245], v[228:229], v[96:97]
	v_pk_fma_f32 v[176:177], v[228:229], v[100:101], v[176:177] neg_lo:[0,0,1] neg_hi:[0,0,1]
	v_pk_fma_f32 v[244:245], v[224:225], v[100:101], v[244:245]
	v_pk_mul_f32 v[178:179], v[226:227], v[98:99]
	v_pk_mul_f32 v[246:247], v[230:231], v[98:99]
	v_pk_fma_f32 v[178:179], v[230:231], v[102:103], v[178:179] neg_lo:[0,0,1] neg_hi:[0,0,1]
	v_pk_fma_f32 v[246:247], v[226:227], v[102:103], v[246:247]
	v_cvt_pk_bf16_f32 v108, v166, v167
	v_cvt_pk_bf16_f32 v109, v168, v169
	v_cvt_pk_bf16_f32 v110, v176, v177
	v_cvt_pk_bf16_f32 v111, v178, v179
	v_cvt_pk_bf16_f32 v104, v240, v241
	v_cvt_pk_bf16_f32 v105, v242, v243
	v_cvt_pk_bf16_f32 v106, v244, v245
	v_cvt_pk_bf16_f32 v107, v246, v247
	v_mad_u32_u24 v128, v162, s57, v248
	global_store_dwordx4 v128, v[108:111], s[0:1]
	global_store_dwordx4 v128, v[104:107], s[0:1] offset:128
	v_add_u32_e32 v178, s16, v158
	v_cmp_gt_i32_e32 vcc, 0x10000, v178
	v_mov_b32_e32 v179, 0
	v_mov_b32_e32 v177, 0x1fff
	v_mov_b32_e32 v176, 0xfff
	v_cndmask_b32_e32 v176, v176, v177, vcc
	v_and_b32_e32 v178, v176, v178
	v_lshlrev_b32_e32 v178, 8, v178
	v_lshl_add_u64 v[176:177], v[142:143], 0, v[178:179]
	global_load_dwordx4 v[216:219], v[176:177], off
	global_load_dwordx4 v[224:227], v[176:177], off offset:16
	v_lshl_add_u64 v[176:177], v[144:145], 0, v[178:179]
	global_load_dwordx4 v[220:223], v[176:177], off
	global_load_dwordx4 v[228:231], v[176:177], off offset:16
	v_mov_b32_e32 v128, v234
	v_pk_mul_f32 v[92:93], v[92:93], v[128:129] op_sel_hi:[1,0]
	v_pk_mul_f32 v[94:95], v[94:95], v[128:129] op_sel_hi:[1,0]
	v_pk_mul_f32 v[88:89], v[88:89], v[128:129] op_sel_hi:[1,0]
	v_pk_mul_f32 v[90:91], v[90:91], v[128:129] op_sel_hi:[1,0]
	v_pk_mul_f32 v[84:85], v[84:85], v[128:129] op_sel_hi:[1,0]
	v_pk_mul_f32 v[86:87], v[86:87], v[128:129] op_sel_hi:[1,0]
	v_pk_mul_f32 v[80:81], v[80:81], v[128:129] op_sel_hi:[1,0]
	v_pk_mul_f32 v[82:83], v[82:83], v[128:129] op_sel_hi:[1,0]
	s_waitcnt vmcnt(6)
	v_pk_mul_f32 v[166:167], v[200:201], v[88:89]
	v_pk_mul_f32 v[240:241], v[204:205], v[88:89]
	v_pk_fma_f32 v[166:167], v[204:205], v[92:93], v[166:167] neg_lo:[0,0,1] neg_hi:[0,0,1]
	v_pk_fma_f32 v[240:241], v[200:201], v[92:93], v[240:241]
	v_pk_mul_f32 v[168:169], v[202:203], v[90:91]
	v_pk_mul_f32 v[242:243], v[206:207], v[90:91]
	v_pk_fma_f32 v[168:169], v[206:207], v[94:95], v[168:169] neg_lo:[0,0,1] neg_hi:[0,0,1]
	v_pk_fma_f32 v[242:243], v[202:203], v[94:95], v[242:243]
	v_pk_mul_f32 v[176:177], v[208:209], v[80:81]
	v_pk_mul_f32 v[244:245], v[212:213], v[80:81]
	v_pk_fma_f32 v[176:177], v[212:213], v[84:85], v[176:177] neg_lo:[0,0,1] neg_hi:[0,0,1]
	v_pk_fma_f32 v[244:245], v[208:209], v[84:85], v[244:245]
	v_pk_mul_f32 v[178:179], v[210:211], v[82:83]
	v_pk_mul_f32 v[246:247], v[214:215], v[82:83]
	v_pk_fma_f32 v[178:179], v[214:215], v[86:87], v[178:179] neg_lo:[0,0,1] neg_hi:[0,0,1]
	v_pk_fma_f32 v[246:247], v[210:211], v[86:87], v[246:247]
	v_cvt_pk_bf16_f32 v92, v166, v167
	v_cvt_pk_bf16_f32 v93, v168, v169
	v_cvt_pk_bf16_f32 v94, v176, v177
	v_cvt_pk_bf16_f32 v95, v178, v179
	v_cvt_pk_bf16_f32 v88, v240, v241
	v_cvt_pk_bf16_f32 v89, v242, v243
	v_cvt_pk_bf16_f32 v90, v244, v245
	v_cvt_pk_bf16_f32 v91, v246, v247
	v_mad_u32_u24 v128, v160, s57, v248
	global_store_dwordx4 v128, v[92:95], s[0:1]
	global_store_dwordx4 v128, v[88:91], s[0:1] offset:128
	v_add_u32_e32 v178, s16, v156
	v_cmp_gt_i32_e32 vcc, 0x10000, v178
	v_mov_b32_e32 v179, 0
	v_mov_b32_e32 v177, 0x1fff
	v_mov_b32_e32 v176, 0xfff
	v_cndmask_b32_e32 v176, v176, v177, vcc
	v_and_b32_e32 v178, v176, v178
	v_lshlrev_b32_e32 v178, 8, v178
	v_lshl_add_u64 v[176:177], v[142:143], 0, v[178:179]
	global_load_dwordx4 v[200:203], v[176:177], off
	global_load_dwordx4 v[208:211], v[176:177], off offset:16
	v_lshl_add_u64 v[176:177], v[144:145], 0, v[178:179]
	global_load_dwordx4 v[204:207], v[176:177], off
	global_load_dwordx4 v[212:215], v[176:177], off offset:16
	v_mov_b32_e32 v128, v235
	v_pk_mul_f32 v[76:77], v[76:77], v[128:129] op_sel_hi:[1,0]
	v_pk_mul_f32 v[78:79], v[78:79], v[128:129] op_sel_hi:[1,0]
	v_pk_mul_f32 v[72:73], v[72:73], v[128:129] op_sel_hi:[1,0]
	v_pk_mul_f32 v[74:75], v[74:75], v[128:129] op_sel_hi:[1,0]
	v_pk_mul_f32 v[68:69], v[68:69], v[128:129] op_sel_hi:[1,0]
	v_pk_mul_f32 v[70:71], v[70:71], v[128:129] op_sel_hi:[1,0]
	v_pk_mul_f32 v[64:65], v[64:65], v[128:129] op_sel_hi:[1,0]
	v_pk_mul_f32 v[66:67], v[66:67], v[128:129] op_sel_hi:[1,0]
	s_waitcnt vmcnt(6)
; __device__ __forceinline__ unsigned pk2(float lo, float hi) { return pg8::cvt_pk_bf16(lo, hi); }
;     __device__ __forceinline__ void operator()(const pg8::f32x4 (&acc)[2][2][4][2], const pg8::Unit& u, int wr, int wc, int fr, int fq) const {
;     ...
;                     u32x4 w1, w2;
; #pragma unroll
;                     for (int n = 0; n < 2; ++n) {
;                         const pg8::f32x4 cs = *(const pg8::f32x4*)(rcos + (size_t)pos * 64 + d0 + 4 * n), sn = *(const pg8::f32x4*)(rsin + (size_t)pos * 64 + d0 + 4 * n);
;                         const pg8::f32x4 t1 = acc[ai][0][m][n] * rs, t2 = acc[ai][1][m][n] * rs;
;                         const pg8::f32x4 o1 = t1 * cs - t2 * sn, o2 = t1 * sn + t2 * cs;
;                         if (n == 0) { w1.x = pk2(o1[0], o1[1]); w1.y = pk2(o1[2], o1[3]); w2.x = pk2(o2[0], o2[1]); w2.y = pk2(o2[2], o2[3]); }
;                         else { w1.z = pk2(o1[0], o1[1]); w1.w = pk2(o1[2], o1[3]); w2.z = pk2(o2[0], o2[1]); w2.w = pk2(o2[2], o2[3]); }
;                     }
;                     *(u32x4*)(P + row * PLD + colr) = w1; *(u32x4*)(P + row * PLD + colr + 64) = w2;
;                     asm volatile("" ::: "memory");
	v_pk_mul_f32 v[166:167], v[216:217], v[72:73]
	v_pk_mul_f32 v[240:241], v[220:221], v[72:73]
	v_pk_fma_f32 v[166:167], v[220:221], v[76:77], v[166:167] neg_lo:[0,0,1] neg_hi:[0,0,1]
	v_pk_fma_f32 v[240:241], v[216:217], v[76:77], v[240:241]
	v_pk_mul_f32 v[168:169], v[218:219], v[74:75]
	v_pk_mul_f32 v[242:243], v[222:223], v[74:75]
	v_pk_fma_f32 v[168:169], v[222:223], v[78:79], v[168:169] neg_lo:[0,0,1] neg_hi:[0,0,1]
	v_pk_fma_f32 v[242:243], v[218:219], v[78:79], v[242:243]
	v_pk_mul_f32 v[176:177], v[224:225], v[64:65]
	v_pk_mul_f32 v[244:245], v[228:229], v[64:65]
	v_pk_fma_f32 v[176:177], v[228:229], v[68:69], v[176:177] neg_lo:[0,0,1] neg_hi:[0,0,1]
	v_pk_fma_f32 v[244:245], v[224:225], v[68:69], v[244:245]
	v_pk_mul_f32 v[178:179], v[226:227], v[66:67]
	v_pk_mul_f32 v[246:247], v[230:231], v[66:67]
	v_pk_fma_f32 v[178:179], v[230:231], v[70:71], v[178:179] neg_lo:[0,0,1] neg_hi:[0,0,1]
	v_pk_fma_f32 v[246:247], v[226:227], v[70:71], v[246:247]
	v_cvt_pk_bf16_f32 v76, v166, v167
	v_cvt_pk_bf16_f32 v77, v168, v169
	v_cvt_pk_bf16_f32 v78, v176, v177
	v_cvt_pk_bf16_f32 v79, v178, v179
	v_cvt_pk_bf16_f32 v72, v240, v241
	v_cvt_pk_bf16_f32 v73, v242, v243
	v_cvt_pk_bf16_f32 v74, v244, v245
	v_cvt_pk_bf16_f32 v75, v246, v247
	v_mad_u32_u24 v128, v158, s57, v248
	global_store_dwordx4 v128, v[76:79], s[0:1]
	global_store_dwordx4 v128, v[72:75], s[0:1] offset:128
	v_add_u32_e32 v178, s16, v154
	v_cmp_gt_i32_e32 vcc, 0x10000, v178
	v_mov_b32_e32 v179, 0
	v_mov_b32_e32 v177, 0x1fff
	v_mov_b32_e32 v176, 0xfff
	v_cndmask_b32_e32 v176, v176, v177, vcc
	v_and_b32_e32 v178, v176, v178
	v_lshlrev_b32_e32 v178, 8, v178
	v_lshl_add_u64 v[176:177], v[142:143], 0, v[178:179]
	global_load_dwordx4 v[216:219], v[176:177], off
	global_load_dwordx4 v[224:227], v[176:177], off offset:16
	v_lshl_add_u64 v[176:177], v[144:145], 0, v[178:179]
	global_load_dwordx4 v[220:223], v[176:177], off
	global_load_dwordx4 v[228:231], v[176:177], off offset:16
	v_mov_b32_e32 v128, v236
	v_pk_mul_f32 v[60:61], v[60:61], v[128:129] op_sel_hi:[1,0]
	v_pk_mul_f32 v[62:63], v[62:63], v[128:129] op_sel_hi:[1,0]
	v_pk_mul_f32 v[56:57], v[56:57], v[128:129] op_sel_hi:[1,0]
	v_pk_mul_f32 v[58:59], v[58:59], v[128:129] op_sel_hi:[1,0]
	v_pk_mul_f32 v[52:53], v[52:53], v[128:129] op_sel_hi:[1,0]
	v_pk_mul_f32 v[54:55], v[54:55], v[128:129] op_sel_hi:[1,0]
	v_pk_mul_f32 v[48:49], v[48:49], v[128:129] op_sel_hi:[1,0]
	v_pk_mul_f32 v[50:51], v[50:51], v[128:129] op_sel_hi:[1,0]
	s_waitcnt vmcnt(6)
	v_pk_mul_f32 v[166:167], v[200:201], v[56:57]
	v_pk_mul_f32 v[240:241], v[204:205], v[56:57]
	v_pk_fma_f32 v[166:167], v[204:205], v[60:61], v[166:167] neg_lo:[0,0,1] neg_hi:[0,0,1]
	v_pk_fma_f32 v[240:241], v[200:201], v[60:61], v[240:241]
	v_pk_mul_f32 v[168:169], v[202:203], v[58:59]
	v_pk_mul_f32 v[242:243], v[206:207], v[58:59]
	v_pk_fma_f32 v[168:169], v[206:207], v[62:63], v[168:169] neg_lo:[0,0,1] neg_hi:[0,0,1]
	v_pk_fma_f32 v[242:243], v[202:203], v[62:63], v[242:243]
	v_pk_mul_f32 v[176:177], v[208:209], v[48:49]
	v_pk_mul_f32 v[244:245], v[212:213], v[48:49]
	v_pk_fma_f32 v[176:177], v[212:213], v[52:53], v[176:177] neg_lo:[0,0,1] neg_hi:[0,0,1]
	v_pk_fma_f32 v[244:245], v[208:209], v[52:53], v[244:245]
	v_pk_mul_f32 v[178:179], v[210:211], v[50:51]
	v_pk_mul_f32 v[246:247], v[214:215], v[50:51]
	v_pk_fma_f32 v[178:179], v[214:215], v[54:55], v[178:179] neg_lo:[0,0,1] neg_hi:[0,0,1]
	v_pk_fma_f32 v[246:247], v[210:211], v[54:55], v[246:247]
	v_cvt_pk_bf16_f32 v60, v166, v167
	v_cvt_pk_bf16_f32 v61, v168, v169
	v_cvt_pk_bf16_f32 v62, v176, v177
	v_cvt_pk_bf16_f32 v63, v178, v179
	v_cvt_pk_bf16_f32 v56, v240, v241
	v_cvt_pk_bf16_f32 v57, v242, v243
	v_cvt_pk_bf16_f32 v58, v244, v245
	v_cvt_pk_bf16_f32 v59, v246, v247
	v_mad_u32_u24 v128, v156, s57, v248
	global_store_dwordx4 v128, v[60:63], s[0:1]
	global_store_dwordx4 v128, v[56:59], s[0:1] offset:128
	v_add_u32_e32 v178, s16, v152
	v_cmp_gt_i32_e32 vcc, 0x10000, v178
	v_mov_b32_e32 v179, 0
	v_mov_b32_e32 v177, 0x1fff
	v_mov_b32_e32 v176, 0xfff
	v_cndmask_b32_e32 v176, v176, v177, vcc
	v_and_b32_e32 v178, v176, v178
	v_lshlrev_b32_e32 v178, 8, v178
	v_lshl_add_u64 v[176:177], v[142:143], 0, v[178:179]
	global_load_dwordx4 v[200:203], v[176:177], off
	global_load_dwordx4 v[208:211], v[176:177], off offset:16
	v_lshl_add_u64 v[176:177], v[144:145], 0, v[178:179]
	global_load_dwordx4 v[204:207], v[176:177], off
	global_load_dwordx4 v[212:215], v[176:177], off offset:16
	v_mov_b32_e32 v128, v237
	v_pk_mul_f32 v[44:45], v[44:45], v[128:129] op_sel_hi:[1,0]
	v_pk_mul_f32 v[46:47], v[46:47], v[128:129] op_sel_hi:[1,0]
	v_pk_mul_f32 v[40:41], v[40:41], v[128:129] op_sel_hi:[1,0]
	v_pk_mul_f32 v[42:43], v[42:43], v[128:129] op_sel_hi:[1,0]
	v_pk_mul_f32 v[36:37], v[36:37], v[128:129] op_sel_hi:[1,0]
	v_pk_mul_f32 v[38:39], v[38:39], v[128:129] op_sel_hi:[1,0]
	v_pk_mul_f32 v[32:33], v[32:33], v[128:129] op_sel_hi:[1,0]
	v_pk_mul_f32 v[34:35], v[34:35], v[128:129] op_sel_hi:[1,0]
	s_waitcnt vmcnt(6)
; __device__ __forceinline__ unsigned pk2(float lo, float hi) { return pg8::cvt_pk_bf16(lo, hi); }
;     __device__ __forceinline__ void operator()(const pg8::f32x4 (&acc)[2][2][4][2], const pg8::Unit& u, int wr, int wc, int fr, int fq) const {
;     ...
;                     u32x4 w1, w2;
; #pragma unroll
;                     for (int n = 0; n < 2; ++n) {
;                         const pg8::f32x4 cs = *(const pg8::f32x4*)(rcos + (size_t)pos * 64 + d0 + 4 * n), sn = *(const pg8::f32x4*)(rsin + (size_t)pos * 64 + d0 + 4 * n);
;                         const pg8::f32x4 t1 = acc[ai][0][m][n] * rs, t2 = acc[ai][1][m][n] * rs;
;                         const pg8::f32x4 o1 = t1 * cs - t2 * sn, o2 = t1 * sn + t2 * cs;
;                         if (n == 0) { w1.x = pk2(o1[0], o1[1]); w1.y = pk2(o1[2], o1[3]); w2.x = pk2(o2[0], o2[1]); w2.y = pk2(o2[2], o2[3]); }
;                         else { w1.z = pk2(o1[0], o1[1]); w1.w = pk2(o1[2], o1[3]); w2.z = pk2(o2[0], o2[1]); w2.w = pk2(o2[2], o2[3]); }
;                     }
;                     *(u32x4*)(P + row * PLD + colr) = w1; *(u32x4*)(P + row * PLD + colr + 64) = w2;
;                     asm volatile("" ::: "memory");
;                 }
	v_pk_mul_f32 v[166:167], v[216:217], v[40:41]
	v_pk_mul_f32 v[240:241], v[220:221], v[40:41]
	v_pk_fma_f32 v[166:167], v[220:221], v[44:45], v[166:167] neg_lo:[0,0,1] neg_hi:[0,0,1]
	v_pk_fma_f32 v[240:241], v[216:217], v[44:45], v[240:241]
	v_pk_mul_f32 v[168:169], v[218:219], v[42:43]
	v_pk_mul_f32 v[242:243], v[222:223], v[42:43]
	v_pk_fma_f32 v[168:169], v[222:223], v[46:47], v[168:169] neg_lo:[0,0,1] neg_hi:[0,0,1]
	v_pk_fma_f32 v[242:243], v[218:219], v[46:47], v[242:243]
	v_pk_mul_f32 v[176:177], v[224:225], v[32:33]
	v_pk_mul_f32 v[244:245], v[228:229], v[32:33]
	v_pk_fma_f32 v[176:177], v[228:229], v[36:37], v[176:177] neg_lo:[0,0,1] neg_hi:[0,0,1]
	v_pk_fma_f32 v[244:245], v[224:225], v[36:37], v[244:245]
	v_pk_mul_f32 v[178:179], v[226:227], v[34:35]
	v_pk_mul_f32 v[246:247], v[230:231], v[34:35]
	v_pk_fma_f32 v[178:179], v[230:231], v[38:39], v[178:179] neg_lo:[0,0,1] neg_hi:[0,0,1]
	v_pk_fma_f32 v[246:247], v[226:227], v[38:39], v[246:247]
	v_cvt_pk_bf16_f32 v44, v166, v167
	v_cvt_pk_bf16_f32 v45, v168, v169
	v_cvt_pk_bf16_f32 v46, v176, v177
	v_cvt_pk_bf16_f32 v47, v178, v179
	v_cvt_pk_bf16_f32 v40, v240, v241
	v_cvt_pk_bf16_f32 v41, v242, v243
	v_cvt_pk_bf16_f32 v42, v244, v245
	v_cvt_pk_bf16_f32 v43, v246, v247
	v_mad_u32_u24 v128, v154, s57, v248
	global_store_dwordx4 v128, v[44:47], s[0:1]
	global_store_dwordx4 v128, v[40:43], s[0:1] offset:128
	v_add_u32_e32 v178, s16, v150
	v_cmp_gt_i32_e32 vcc, 0x10000, v178
	v_mov_b32_e32 v179, 0
	v_mov_b32_e32 v177, 0x1fff
	v_mov_b32_e32 v176, 0xfff
	v_cndmask_b32_e32 v176, v176, v177, vcc
	v_and_b32_e32 v178, v176, v178
	v_lshlrev_b32_e32 v178, 8, v178
	v_lshl_add_u64 v[176:177], v[142:143], 0, v[178:179]
	global_load_dwordx4 v[216:219], v[176:177], off
	global_load_dwordx4 v[224:227], v[176:177], off offset:16
	v_lshl_add_u64 v[176:177], v[144:145], 0, v[178:179]
	global_load_dwordx4 v[220:223], v[176:177], off
	global_load_dwordx4 v[228:231], v[176:177], off offset:16
	v_mov_b32_e32 v128, v238
	v_pk_mul_f32 v[28:29], v[28:29], v[128:129] op_sel_hi:[1,0]
	v_pk_mul_f32 v[30:31], v[30:31], v[128:129] op_sel_hi:[1,0]
	v_pk_mul_f32 v[24:25], v[24:25], v[128:129] op_sel_hi:[1,0]
	v_pk_mul_f32 v[26:27], v[26:27], v[128:129] op_sel_hi:[1,0]
	v_pk_mul_f32 v[20:21], v[20:21], v[128:129] op_sel_hi:[1,0]
	v_pk_mul_f32 v[22:23], v[22:23], v[128:129] op_sel_hi:[1,0]
	v_pk_mul_f32 v[16:17], v[16:17], v[128:129] op_sel_hi:[1,0]
	v_pk_mul_f32 v[18:19], v[18:19], v[128:129] op_sel_hi:[1,0]
	s_waitcnt vmcnt(6)
	v_pk_mul_f32 v[166:167], v[200:201], v[24:25]
	v_pk_mul_f32 v[240:241], v[204:205], v[24:25]
	v_pk_fma_f32 v[166:167], v[204:205], v[28:29], v[166:167] neg_lo:[0,0,1] neg_hi:[0,0,1]
	v_pk_fma_f32 v[240:241], v[200:201], v[28:29], v[240:241]
	v_pk_mul_f32 v[168:169], v[202:203], v[26:27]
	v_pk_mul_f32 v[242:243], v[206:207], v[26:27]
	v_pk_fma_f32 v[168:169], v[206:207], v[30:31], v[168:169] neg_lo:[0,0,1] neg_hi:[0,0,1]
	v_pk_fma_f32 v[242:243], v[202:203], v[30:31], v[242:243]
	v_pk_mul_f32 v[176:177], v[208:209], v[16:17]
	v_pk_mul_f32 v[244:245], v[212:213], v[16:17]
	v_pk_fma_f32 v[176:177], v[212:213], v[20:21], v[176:177] neg_lo:[0,0,1] neg_hi:[0,0,1]
	v_pk_fma_f32 v[244:245], v[208:209], v[20:21], v[244:245]
	v_pk_mul_f32 v[178:179], v[210:211], v[18:19]
	v_pk_mul_f32 v[246:247], v[214:215], v[18:19]
	v_pk_fma_f32 v[178:179], v[214:215], v[22:23], v[178:179] neg_lo:[0,0,1] neg_hi:[0,0,1]
	v_pk_fma_f32 v[246:247], v[210:211], v[22:23], v[246:247]
	v_cvt_pk_bf16_f32 v28, v166, v167
	v_cvt_pk_bf16_f32 v29, v168, v169
	v_cvt_pk_bf16_f32 v30, v176, v177
	v_cvt_pk_bf16_f32 v31, v178, v179
	v_cvt_pk_bf16_f32 v24, v240, v241
	v_cvt_pk_bf16_f32 v25, v242, v243
	v_cvt_pk_bf16_f32 v26, v244, v245
	v_cvt_pk_bf16_f32 v27, v246, v247
	v_mad_u32_u24 v128, v152, s57, v248
	global_store_dwordx4 v128, v[28:31], s[0:1]
	global_store_dwordx4 v128, v[24:27], s[0:1] offset:128
	v_mov_b32_e32 v128, v239
	v_pk_mul_f32 v[12:13], v[12:13], v[128:129] op_sel_hi:[1,0]
	v_pk_mul_f32 v[14:15], v[14:15], v[128:129] op_sel_hi:[1,0]
	v_pk_mul_f32 v[8:9], v[8:9], v[128:129] op_sel_hi:[1,0]
	v_pk_mul_f32 v[10:11], v[10:11], v[128:129] op_sel_hi:[1,0]
	v_pk_mul_f32 v[4:5], v[4:5], v[128:129] op_sel_hi:[1,0]
	v_pk_mul_f32 v[6:7], v[6:7], v[128:129] op_sel_hi:[1,0]
	v_pk_mul_f32 v[0:1], v[0:1], v[128:129] op_sel_hi:[1,0]
	v_pk_mul_f32 v[2:3], v[2:3], v[128:129] op_sel_hi:[1,0]
	s_waitcnt vmcnt(2)
	v_pk_mul_f32 v[166:167], v[216:217], v[8:9]
	v_pk_mul_f32 v[240:241], v[220:221], v[8:9]
	v_pk_fma_f32 v[166:167], v[220:221], v[12:13], v[166:167] neg_lo:[0,0,1] neg_hi:[0,0,1]
	v_pk_fma_f32 v[240:241], v[216:217], v[12:13], v[240:241]
	v_pk_mul_f32 v[168:169], v[218:219], v[10:11]
	v_pk_mul_f32 v[242:243], v[222:223], v[10:11]
	v_pk_fma_f32 v[168:169], v[222:223], v[14:15], v[168:169] neg_lo:[0,0,1] neg_hi:[0,0,1]
	v_pk_fma_f32 v[242:243], v[218:219], v[14:15], v[242:243]
	v_pk_mul_f32 v[176:177], v[224:225], v[0:1]
	v_pk_mul_f32 v[244:245], v[228:229], v[0:1]
	v_pk_fma_f32 v[176:177], v[228:229], v[4:5], v[176:177] neg_lo:[0,0,1] neg_hi:[0,0,1]
	v_pk_fma_f32 v[244:245], v[224:225], v[4:5], v[244:245]
	v_pk_mul_f32 v[178:179], v[226:227], v[2:3]
	v_pk_mul_f32 v[246:247], v[230:231], v[2:3]
	v_pk_fma_f32 v[178:179], v[230:231], v[6:7], v[178:179] neg_lo:[0,0,1] neg_hi:[0,0,1]
	v_pk_fma_f32 v[246:247], v[226:227], v[6:7], v[246:247]
	v_cvt_pk_bf16_f32 v12, v166, v167
	v_cvt_pk_bf16_f32 v13, v168, v169
	v_cvt_pk_bf16_f32 v14, v176, v177
	v_cvt_pk_bf16_f32 v15, v178, v179
	v_cvt_pk_bf16_f32 v8, v240, v241
	v_cvt_pk_bf16_f32 v9, v242, v243
	v_cvt_pk_bf16_f32 v10, v244, v245
	v_cvt_pk_bf16_f32 v11, v246, v247
	v_mad_u32_u24 v128, v150, s57, v248
	global_store_dwordx4 v128, v[12:15], s[0:1]
	global_store_dwordx4 v128, v[8:11], s[0:1] offset:128
	s_andn2_b64 vcc, exec, s[38:39]
	s_mov_b64 s[0:1], -1
	s_cbranch_vccnz .LBB0_171
